# hoisted first PV V-fragment LDS reads above softmax exps (v64-79), negm copies moved to loop-exit edge; on top of v35
# speedup vs baseline: 1.0044x; 1.0044x over previous
; __device__ __forceinline__ void partialSM(f32x16& p0, f32x16& p1, float& m_ref, f32x16& negm, float& alpha, bool first) {
;     constexpr float THR2 = THR * 1.4426950408889634f;
;     float ma = p0[0], mb = p0[8], mc = p1[0], md = p1[8];
; #pragma unroll
;     for (int r = 1; r < 8; ++r) { ma = fmaxf(ma, p0[r]); mb = fmaxf(mb, p0[8 + r]); mc = fmaxf(mc, p1[r]); md = fmaxf(md, p1[8 + r]); }
;     float pmax = fmaxf(fmaxf(ma, mb), fmaxf(mc, md));
;     { auto rr = __builtin_amdgcn_permlane32_swap(__float_as_uint(pmax), __float_as_uint(pmax), false, false);
;       pmax = fmaxf(__uint_as_float(rr[0]), __uint_as_float(rr[1])); }
;     if (__builtin_expect(!first && __all(pmax <= THR2), 1)) { alpha = 1.f; }
; __device__ __forceinline__ void qkt(f32x16& p0, f32x16& p1, const char* Ks, const char* Krs, const bf16x8* qr, const char* qro, int r32, int hi, const f32x16& negm) {
;     p0 = negm; p1 = negm;
; #pragma unroll
;     for (int d0 = 0; d0 < 8; ++d0) { const int cb = (d0 * 16 + hi * 8) * 2;
;         const bf16x8 b0 = *reinterpret_cast<const bf16x8*>(Ks + KSWZ(r32, cb));
;         const bf16x8 b1 = *reinterpret_cast<const bf16x8*>(Ks + KSWZ(32 + r32, cb));
;         p0 = __builtin_amdgcn_mfma_f32_32x32x16_bf16(b0, qr[d0], p0, 0, 0, 0);
;         p1 = __builtin_amdgcn_mfma_f32_32x32x16_bf16(b1, qr[d0], p1, 0, 0, 0); }
; #pragma unroll
;     for (int d0 = 0; d0 < 4; ++d0) { const int cb = (d0 * 16 + hi * 8) * 2;
;         const bf16x8 b0 = *reinterpret_cast<const bf16x8*>(Krs + KRSWZ(r32, cb));
;         const bf16x8 b1 = *reinterpret_cast<const bf16x8*>(Krs + KRSWZ(32 + r32, cb));
;         const bf16x8 qf = qr[8 + d0];
;         p0 = __builtin_amdgcn_mfma_f32_32x32x16_bf16(b0, qf, p0, 0, 0, 0);
;         p1 = __builtin_amdgcn_mfma_f32_32x32x16_bf16(b1, qf, p1, 0, 0, 0); }
; }
.LBB0_396:
	s_lshl_b32 s74, vcc_lo, 14
	v_add_u32_e32 v64, s74, v228
	s_lshl_b32 s72, s71, 14
	v_readfirstlane_b32 s7, v64
	s_mov_b32 s10, m0
	s_mov_b32 m0, s7
	s_nop 0
	global_load_lds_dwordx4 v[208:209], off
	s_mov_b32 m0, s10
	s_addk_i32 s7, 0x400
	v_add_u32_e32 v64, s72, v213
	s_mov_b32 s10, m0
	s_mov_b32 m0, s7
	s_nop 0
	global_load_lds_dwordx4 v[206:207], off
	s_mov_b32 m0, s10
	s_lshl_b32 s73, s71, 13
	v_readfirstlane_b32 s7, v64
	s_mov_b32 s10, m0
	s_mov_b32 m0, s7
	s_nop 0
	global_load_lds_dwordx4 v[204:205], off
	s_mov_b32 m0, s10
	s_addk_i32 s7, 0x400
	v_add_u32_e32 v64, s73, v212
	s_mov_b32 s6, s70
	s_mov_b32 s10, m0
	s_mov_b32 m0, s7
	s_nop 0
	global_load_lds_dwordx4 v[202:203], off
	s_mov_b32 m0, s10
	v_readfirstlane_b32 s7, v64
	s_mov_b32 s10, m0
	s_mov_b32 m0, s7
	s_nop 0
	global_load_lds_dwordx4 v[200:201], off
	s_mov_b32 m0, s10
	s_lshl_b32 s7, s6, 14
	s_add_i32 s10, s7, 0
	v_add3_u32 v68, s10, v227, v211
	ds_read_b128 v[64:67], v68
	s_waitcnt lgkmcnt(0)
	v_mfma_f32_32x32x16_bf16 v[112:127], v[64:67], v[128:131], v[80:95]
	ds_read_b128 v[64:67], v68 offset:8192
	v_add3_u32 v68, s10, v226, v211
	s_lshl_b32 s11, s6, 13
	s_mov_b32 s70, vcc_lo
	s_waitcnt lgkmcnt(0)
	v_mfma_f32_32x32x16_bf16 v[96:111], v[64:67], v[128:131], v[80:95]
	ds_read_b128 v[64:67], v68
	s_waitcnt lgkmcnt(0)
	v_mfma_f32_32x32x16_bf16 v[112:127], v[64:67], v[132:135], v[112:127]
	ds_read_b128 v[64:67], v68 offset:8192
	v_add3_u32 v68, s10, v225, v211
	s_waitcnt lgkmcnt(0)
	v_mfma_f32_32x32x16_bf16 v[96:111], v[64:67], v[132:135], v[96:111]
	ds_read_b128 v[64:67], v68
	s_waitcnt lgkmcnt(0)
	v_mfma_f32_32x32x16_bf16 v[112:127], v[64:67], v[136:139], v[112:127]
	ds_read_b128 v[64:67], v68 offset:8192
	v_add3_u32 v68, s10, v224, v211
	s_waitcnt lgkmcnt(0)
	v_mfma_f32_32x32x16_bf16 v[96:111], v[64:67], v[136:139], v[96:111]
	ds_read_b128 v[64:67], v68
	s_waitcnt lgkmcnt(0)
	v_mfma_f32_32x32x16_bf16 v[112:127], v[64:67], v[140:143], v[112:127]
	ds_read_b128 v[64:67], v68 offset:8192
	v_add3_u32 v68, s10, v223, v211
	s_waitcnt lgkmcnt(0)
	v_mfma_f32_32x32x16_bf16 v[96:111], v[64:67], v[140:143], v[96:111]
	ds_read_b128 v[64:67], v68
	s_waitcnt lgkmcnt(0)
	v_mfma_f32_32x32x16_bf16 v[112:127], v[64:67], v[144:147], v[112:127]
	ds_read_b128 v[64:67], v68 offset:8192
	v_add3_u32 v68, s10, v222, v211
	s_waitcnt lgkmcnt(0)
	v_mfma_f32_32x32x16_bf16 v[96:111], v[64:67], v[144:147], v[96:111]
	ds_read_b128 v[64:67], v68
	s_waitcnt lgkmcnt(0)
	v_mfma_f32_32x32x16_bf16 v[112:127], v[64:67], v[148:151], v[112:127]
	ds_read_b128 v[64:67], v68 offset:8192
	v_add3_u32 v68, s10, v221, v211
	s_waitcnt lgkmcnt(0)
	v_mfma_f32_32x32x16_bf16 v[96:111], v[64:67], v[148:151], v[96:111]
	ds_read_b128 v[64:67], v68
	s_waitcnt lgkmcnt(0)
	v_mfma_f32_32x32x16_bf16 v[112:127], v[64:67], v[152:155], v[112:127]
	ds_read_b128 v[64:67], v68 offset:8192
	v_add3_u32 v68, s10, v220, v211
	s_sub_i32 s10, s10, s11
	s_waitcnt lgkmcnt(0)
	v_mfma_f32_32x32x16_bf16 v[96:111], v[64:67], v[152:155], v[96:111]
	ds_read_b128 v[64:67], v68
	s_waitcnt lgkmcnt(0)
	v_mfma_f32_32x32x16_bf16 v[112:127], v[64:67], v[156:159], v[112:127]
	ds_read_b128 v[64:67], v68 offset:8192
	v_add3_u32 v68, s10, v219, v215
	s_waitcnt lgkmcnt(0)
	v_mfma_f32_32x32x16_bf16 v[96:111], v[64:67], v[156:159], v[96:111]
	ds_read_b128 v[64:67], v68 offset:49152
	s_waitcnt lgkmcnt(0)
	v_mfma_f32_32x32x16_bf16 v[112:127], v[64:67], v[164:167], v[112:127]
	ds_read_b128 v[64:67], v68 offset:53248
	v_add3_u32 v68, s10, v218, v215
	s_waitcnt lgkmcnt(0)
	v_mfma_f32_32x32x16_bf16 v[96:111], v[64:67], v[164:167], v[96:111]
	ds_read_b128 v[64:67], v68 offset:49152
	s_waitcnt lgkmcnt(0)
	v_mfma_f32_32x32x16_bf16 v[112:127], v[64:67], v[172:175], v[112:127]
	ds_read_b128 v[64:67], v68 offset:53248
	v_add3_u32 v68, s10, v217, v215
	s_waitcnt lgkmcnt(0)
	v_mfma_f32_32x32x16_bf16 v[96:111], v[64:67], v[172:175], v[96:111]
	ds_read_b128 v[64:67], v68 offset:49152
	s_waitcnt lgkmcnt(0)
	v_mfma_f32_32x32x16_bf16 v[112:127], v[64:67], v[160:163], v[112:127]
	ds_read_b128 v[64:67], v68 offset:53248
	v_add3_u32 v68, s10, v216, v215
	s_waitcnt lgkmcnt(0)
	v_mfma_f32_32x32x16_bf16 v[96:111], v[64:67], v[160:163], v[96:111]
	ds_read_b128 v[64:67], v68 offset:49152
	s_waitcnt lgkmcnt(0)
	v_mfma_f32_32x32x16_bf16 v[112:127], v[64:67], v[168:171], v[112:127]
	ds_read_b128 v[64:67], v68 offset:53248
	s_waitcnt lgkmcnt(0)
	v_mfma_f32_32x32x16_bf16 v[96:111], v[64:67], v[168:171], v[96:111]
	s_nop 8
	v_max_f32_e32 v68, v113, v113
	v_max_f32_e32 v69, v112, v112
	v_max_f32_e32 v68, v69, v68
	v_max_f32_e32 v69, v121, v121
	v_max_f32_e32 v70, v120, v120
	v_max_f32_e32 v69, v70, v69
	v_max3_f32 v66, v68, v114, v115
	v_max_f32_e32 v64, v105, v105
	v_max_f32_e32 v65, v104, v104
	v_max_f32_e32 v64, v65, v64
	v_max3_f32 v65, v96, v97, v98
	v_max3_f32 v64, v64, v106, v107
	v_max3_f32 v67, v69, v122, v123
	v_max3_f32 v65, v65, v99, v100
	v_max3_f32 v64, v64, v108, v109
	v_max3_f32 v66, v66, v116, v117
	v_max3_f32 v67, v67, v124, v125
	v_max3_f32 v65, v65, v101, v102
	v_max3_f32 v64, v64, v110, v111
	v_max3_f32 v66, v66, v118, v119
	v_max3_f32 v67, v67, v126, v127
	v_max3_f32 v64, v65, v103, v64
	v_max3_f32 v64, v66, v67, v64
	v_mov_b32_e32 v65, v64
	s_nop 1
	v_permlane32_swap_b32_e32 v64, v65
	v_max_f32_e32 v65, v65, v65
	v_max_f32_e32 v64, v64, v64
	v_max_f32_e32 v64, v64, v65
	v_cmp_ge_f32_e32 vcc, s92, v64
	s_cmp_eq_u64 vcc, exec
	s_cbranch_scc0 .LBB0_404
	v_mov_b32_e32 v229, 1.0
; __device__ __forceinline__ void finishSM(f32x16& p0, f32x16& p1, float alpha, float& l_reg, bf16x8& pa0, bf16x8& pa1, bf16x8& pa2, bf16x8& pa3) {
; #pragma unroll
;     for (int r = 0; r < 16; ++r) p1[r] = __builtin_amdgcn_exp2f(p1[r]);
;     float sa = p0[0], sb = p0[8], sc = p1[0], sd = p1[8];
; #pragma unroll
;     for (int r = 1; r < 8; ++r) { sa += p0[r]; sb += p0[8 + r]; sc += p1[r]; sd += p1[8 + r]; }
;     float ps = (sa + sb) + (sc + sd);
;     { auto rr = __builtin_amdgcn_permlane32_swap(__float_as_uint(ps), __float_as_uint(ps), false, false);
;       ps = __uint_as_float(rr[0]) + __uint_as_float(rr[1]); }
;     l_reg = l_reg * alpha + ps;
;     ...
;     PK4(p0, 0, pa0); PK4(p0, 8, pa1); PK4(p1, 0, pa2); PK4(p1, 8, pa3);
; template <int D0> __device__ __forceinline__ void pv_one(f32x16& od, int vb, bf16x8 pa0, bf16x8 pa1, bf16x8 pa2, bf16x8 pa3) {
;     const s16x4 l0 = tr_read<v_rd_off(D0, 0, 0)>(vb), h0 = tr_read<v_rd_off(D0, 0, 1)>(vb), l1 = tr_read<v_rd_off(D0, 1, 0)>(vb), h1 = tr_read<v_rd_off(D0, 1, 1)>(vb);
.LBB0_398:
	v_add_u32_e32 v245, s7, v214
	ds_read_b64_tr_b16 v[64:65], v245 offset:0
	ds_read_b64_tr_b16 v[66:67], v245 offset:0x800
	ds_read_b64_tr_b16 v[68:69], v245 offset:0x1000
	ds_read_b64_tr_b16 v[70:71], v245 offset:0x1800
	ds_read_b64_tr_b16 v[72:73], v245 offset:0x2000
	ds_read_b64_tr_b16 v[74:75], v245 offset:0x2800
	ds_read_b64_tr_b16 v[76:77], v245 offset:0x3000
	ds_read_b64_tr_b16 v[78:79], v245 offset:0x3800
	v_exp_f32_e32 v230, v112
	v_exp_f32_e32 v231, v113
	v_exp_f32_e32 v120, v120
	v_exp_f32_e32 v121, v121
	v_exp_f32_e32 v232, v96
	v_exp_f32_e32 v233, v97
	v_exp_f32_e32 v236, v104
	v_exp_f32_e32 v237, v105
	v_exp_f32_e32 v114, v114
	v_exp_f32_e32 v122, v122
	v_exp_f32_e32 v234, v98
	v_exp_f32_e32 v238, v106
	v_exp_f32_e32 v115, v115
	v_exp_f32_e32 v123, v123
	v_exp_f32_e32 v235, v99
	v_exp_f32_e32 v239, v107
	v_exp_f32_e32 v116, v116
	v_exp_f32_e32 v124, v124
	v_exp_f32_e32 v100, v100
	v_exp_f32_e32 v240, v108
	v_exp_f32_e32 v117, v117
	v_exp_f32_e32 v125, v125
	v_exp_f32_e32 v101, v101
	v_exp_f32_e32 v241, v109
	v_add_f32_e32 v96, v231, v230
	v_add_f32_e32 v97, v121, v120
	v_add_f32_e32 v98, v233, v232
	v_add_f32_e32 v99, v237, v236
	v_exp_f32_e32 v118, v118
	v_exp_f32_e32 v126, v126
	v_exp_f32_e32 v102, v102
	v_exp_f32_e32 v242, v110
	v_add_f32_e32 v96, v114, v96
	v_add_f32_e32 v97, v122, v97
	v_add_f32_e32 v98, v234, v98
	v_add_f32_e32 v99, v238, v99
	v_exp_f32_e32 v119, v119
	v_exp_f32_e32 v127, v127
	v_exp_f32_e32 v103, v103
	v_exp_f32_e32 v243, v111
	v_add_f32_e32 v96, v115, v96
	v_add_f32_e32 v97, v123, v97
	v_add_f32_e32 v98, v235, v98
	v_add_f32_e32 v99, v239, v99
	v_add_f32_e32 v96, v116, v96
	v_add_f32_e32 v97, v124, v97
	v_add_f32_e32 v98, v100, v98
	v_add_f32_e32 v99, v240, v99
	v_add_f32_e32 v96, v117, v96
	v_add_f32_e32 v97, v125, v97
	v_add_f32_e32 v98, v101, v98
	v_add_f32_e32 v99, v241, v99
	v_add_f32_e32 v96, v118, v96
	v_add_f32_e32 v97, v126, v97
	v_add_f32_e32 v98, v102, v98
	v_add_f32_e32 v99, v242, v99
	v_add_f32_e32 v96, v119, v96
	v_add_f32_e32 v97, v127, v97
	v_add_f32_e32 v98, v103, v98
	v_add_f32_e32 v99, v243, v99
	v_add_f32_e32 v96, v97, v96
	v_add_f32_e32 v97, v99, v98
	v_add_f32_e32 v112, v97, v96
	v_mov_b32_e32 v113, v112
	v_cvt_pk_bf16_f32 v96, v230, v231
	v_cvt_pk_bf16_f32 v97, v114, v115
	v_cvt_pk_bf16_f32 v98, v116, v117
	v_cvt_pk_bf16_f32 v99, v118, v119
	v_cvt_pk_bf16_f32 v104, v120, v121
	v_cvt_pk_bf16_f32 v105, v122, v123
	v_cvt_pk_bf16_f32 v106, v124, v125
	v_cvt_pk_bf16_f32 v107, v126, v127
	v_cvt_pk_bf16_f32 v108, v232, v233
	v_cvt_pk_bf16_f32 v109, v234, v235
	v_cvt_pk_bf16_f32 v110, v100, v101
	v_cvt_pk_bf16_f32 v111, v102, v103
	v_cvt_pk_bf16_f32 v100, v236, v237
	v_cvt_pk_bf16_f32 v101, v238, v239
	v_cvt_pk_bf16_f32 v102, v240, v241
	v_cvt_pk_bf16_f32 v103, v242, v243
	s_nop 1
	v_permlane32_swap_b32_e32 v112, v113
	v_permlane32_swap_b32_e32 v96, v98
	v_permlane32_swap_b32_e32 v97, v99
	v_permlane32_swap_b32_e32 v104, v106
	v_permlane32_swap_b32_e32 v105, v107
	v_permlane32_swap_b32_e32 v108, v110
	v_permlane32_swap_b32_e32 v109, v111
	v_permlane32_swap_b32_e32 v100, v102
	v_permlane32_swap_b32_e32 v101, v103
	v_cmp_gt_f32_e32 vcc, 1.0, v229
	s_cbranch_vccz .LBB0_402
	s_and_saveexec_b64 s[68:69], s[0:1]
	ds_write_b32 v187, v229 offset:128
	s_or_b64 exec, exec, s[68:69]
	s_waitcnt lgkmcnt(0)
	v_add_u32_e32 v126, v183, v184
	ds_read_b128 v[114:117], v126 offset:224
	ds_read_b128 v[118:121], v126 offset:192
	ds_read_b128 v[122:125], v126 offset:160
	ds_read_b128 v[230:233], v126 offset:128
	s_waitcnt lgkmcnt(3)
	v_pk_mul_f32 v[12:13], v[12:13], v[114:115]
	s_waitcnt lgkmcnt(2)
	v_pk_mul_f32 v[8:9], v[8:9], v[118:119]
	s_waitcnt lgkmcnt(1)
	v_pk_mul_f32 v[4:5], v[4:5], v[122:123]
	v_pk_mul_f32 v[14:15], v[14:15], v[116:117]
	v_pk_mul_f32 v[10:11], v[10:11], v[120:121]
	v_pk_mul_f32 v[6:7], v[6:7], v[124:125]
	s_waitcnt lgkmcnt(0)
	v_pk_mul_f32 v[2:3], v[2:3], v[232:233]
	v_pk_mul_f32 v[0:1], v[0:1], v[230:231]
	v_pk_mul_f32 v[28:29], v[28:29], v[114:115]
	v_pk_mul_f32 v[24:25], v[24:25], v[118:119]
	v_pk_mul_f32 v[20:21], v[20:21], v[122:123]
	v_pk_mul_f32 v[30:31], v[30:31], v[116:117]
	v_pk_mul_f32 v[26:27], v[26:27], v[120:121]
	v_pk_mul_f32 v[22:23], v[22:23], v[124:125]
	v_pk_mul_f32 v[18:19], v[18:19], v[232:233]
	v_pk_mul_f32 v[16:17], v[16:17], v[230:231]
	v_pk_mul_f32 v[44:45], v[44:45], v[114:115]
	v_pk_mul_f32 v[40:41], v[40:41], v[118:119]
	v_pk_mul_f32 v[36:37], v[36:37], v[122:123]
	v_pk_mul_f32 v[46:47], v[46:47], v[116:117]
	v_pk_mul_f32 v[42:43], v[42:43], v[120:121]
	v_pk_mul_f32 v[38:39], v[38:39], v[124:125]
	v_pk_mul_f32 v[34:35], v[34:35], v[232:233]
	v_pk_mul_f32 v[32:33], v[32:33], v[230:231]
	v_pk_mul_f32 v[60:61], v[60:61], v[114:115]
	v_pk_mul_f32 v[56:57], v[56:57], v[118:119]
	v_pk_mul_f32 v[52:53], v[52:53], v[122:123]
	v_pk_mul_f32 v[62:63], v[62:63], v[116:117]
	v_pk_mul_f32 v[58:59], v[58:59], v[120:121]
	v_pk_mul_f32 v[54:55], v[54:55], v[124:125]
	v_pk_mul_f32 v[50:51], v[50:51], v[232:233]
	v_pk_mul_f32 v[48:49], v[48:49], v[230:231]
; #define SBAR() __builtin_amdgcn_sched_barrier(0)
; __device__ __forceinline__ void partialSM(f32x16& p0, f32x16& p1, float& m_ref, f32x16& negm, float& alpha, bool first) {
;     ...
;     else { const float d = first ? pmax : fmaxf(pmax, 0.f); m_ref += d; alpha = first ? 1.f : __builtin_amdgcn_exp2f(-d);
; #pragma unroll
;         for (int r = 0; r < 16; ++r) { p0[r] -= d; p1[r] -= d; }
; #pragma unroll
;         for (int r = 0; r < 16; ++r) negm[r] = -m_ref; }
; template <int D0> __device__ __forceinline__ void pv_one(f32x16& od, int vb, bf16x8 pa0, bf16x8 pa1, bf16x8 pa2, bf16x8 pa3) {
;     const s16x4 l0 = tr_read<v_rd_off(D0, 0, 0)>(vb), h0 = tr_read<v_rd_off(D0, 0, 1)>(vb), l1 = tr_read<v_rd_off(D0, 1, 0)>(vb), h1 = tr_read<v_rd_off(D0, 1, 1)>(vb);
;     const s16x4 l2 = tr_read<v_rd_off(D0, 2, 0)>(vb), h2 = tr_read<v_rd_off(D0, 2, 1)>(vb), l3 = tr_read<v_rd_off(D0, 3, 0)>(vb), h3 = tr_read<v_rd_off(D0, 3, 1)>(vb);
;     asm volatile("s_waitcnt lgkmcnt(0)" ::: "memory"); SBAR();
;     ...
;     od = __builtin_amdgcn_mfma_f32_32x32x16_bf16(pa0, PK(l0, h0), od, 0, 0, 0);
;     od = __builtin_amdgcn_mfma_f32_32x32x16_bf16(pa1, PK(l1, h1), od, 0, 0, 0);
;     od = __builtin_amdgcn_mfma_f32_32x32x16_bf16(pa2, PK(l2, h2), od, 0, 0, 0);
;     od = __builtin_amdgcn_mfma_f32_32x32x16_bf16(pa3, PK(l3, h3), od, 0, 0, 0);
;     ...
; }
; __device__ __forceinline__ void pv_d0(f32x16* o, int vb, bf16x8 pa0, bf16x8 pa1, bf16x8 pa2, bf16x8 pa3) {
;     pv_one<0>(o[0], vb, pa0, pa1, pa2, pa3); pv_one<1>(o[1], vb, pa0, pa1, pa2, pa3); pv_one<2>(o[2], vb, pa0, pa1, pa2, pa3); pv_one<3>(o[3], vb, pa0, pa1, pa2, pa3);
.LBB0_402:
	v_add_f32_e32 v112, v112, v113
	v_add_u32_e32 v113, s7, v214
	s_waitcnt lgkmcnt(0)
	v_fmac_f32_e32 v112, v198, v229
	v_mfma_f32_32x32x16_bf16 v[0:15], v[96:99], v[64:67], v[0:15]
	ds_read_b64_tr_b16 v[114:115], v113 offset:0x200
	ds_read_b64_tr_b16 v[116:117], v113 offset:0xa00
	v_mfma_f32_32x32x16_bf16 v[0:15], v[104:107], v[68:71], v[0:15]
	ds_read_b64_tr_b16 v[118:119], v113 offset:0x1200
	ds_read_b64_tr_b16 v[120:121], v113 offset:0x1a00
	v_mfma_f32_32x32x16_bf16 v[0:15], v[108:111], v[72:75], v[0:15]
	ds_read_b64_tr_b16 v[122:123], v113 offset:0x2200
	ds_read_b64_tr_b16 v[124:125], v113 offset:0x2a00
	v_mfma_f32_32x32x16_bf16 v[0:15], v[100:103], v[76:79], v[0:15]
	ds_read_b64_tr_b16 v[230:231], v113 offset:0x3200
	ds_read_b64_tr_b16 v[232:233], v113 offset:0x3a00
	s_waitcnt lgkmcnt(0)
	v_mfma_f32_32x32x16_bf16 v[16:31], v[96:99], v[114:117], v[16:31]
	ds_read_b64_tr_b16 v[114:115], v113 offset:0x400
	ds_read_b64_tr_b16 v[116:117], v113 offset:0xc00
	v_mfma_f32_32x32x16_bf16 v[16:31], v[104:107], v[118:121], v[16:31]
	ds_read_b64_tr_b16 v[118:119], v113 offset:0x1400
	ds_read_b64_tr_b16 v[120:121], v113 offset:0x1c00
	v_mfma_f32_32x32x16_bf16 v[16:31], v[108:111], v[122:125], v[16:31]
	ds_read_b64_tr_b16 v[122:123], v113 offset:0x2400
	ds_read_b64_tr_b16 v[124:125], v113 offset:0x2c00
	v_mfma_f32_32x32x16_bf16 v[16:31], v[100:103], v[230:233], v[16:31]
	ds_read_b64_tr_b16 v[230:231], v113 offset:0x3400
	ds_read_b64_tr_b16 v[232:233], v113 offset:0x3c00
	s_waitcnt lgkmcnt(0)
	v_mfma_f32_32x32x16_bf16 v[32:47], v[96:99], v[114:117], v[32:47]
	ds_read_b64_tr_b16 v[114:115], v113 offset:0x600
	ds_read_b64_tr_b16 v[116:117], v113 offset:0xe00
	v_mfma_f32_32x32x16_bf16 v[32:47], v[104:107], v[118:121], v[32:47]
	ds_read_b64_tr_b16 v[118:119], v113 offset:0x1600
	ds_read_b64_tr_b16 v[120:121], v113 offset:0x1e00
	v_mfma_f32_32x32x16_bf16 v[32:47], v[108:111], v[122:125], v[32:47]
	ds_read_b64_tr_b16 v[122:123], v113 offset:0x2600
	ds_read_b64_tr_b16 v[124:125], v113 offset:0x2e00
	v_mfma_f32_32x32x16_bf16 v[32:47], v[100:103], v[230:233], v[32:47]
	ds_read_b64_tr_b16 v[230:231], v113 offset:0x3600
	ds_read_b64_tr_b16 v[232:233], v113 offset:0x3e00
	s_waitcnt lgkmcnt(0)
	v_mfma_f32_32x32x16_bf16 v[48:63], v[96:99], v[114:117], v[48:63]
	s_waitcnt vmcnt(3) lgkmcnt(0)
	s_barrier
	s_add_i32 s28, s28, 1
	v_lshl_add_u64 v[200:201], v[200:201], 0, s[38:39]
	v_lshl_add_u64 v[202:203], v[202:203], 0, s[36:37]
	v_lshl_add_u64 v[204:205], v[204:205], 0, s[36:37]
	v_lshl_add_u64 v[206:207], v[206:207], 0, s[36:37]
	v_lshl_add_u64 v[208:209], v[208:209], 0, s[36:37]
	v_mfma_f32_32x32x16_bf16 v[48:63], v[104:107], v[118:121], v[48:63]
	s_cmp_eq_u32 s33, s28
	v_mfma_f32_32x32x16_bf16 v[48:63], v[108:111], v[122:125], v[48:63]
	v_mfma_f32_32x32x16_bf16 v[48:63], v[100:103], v[230:233], v[48:63]
	s_cbranch_scc1 .LBB0_405
	s_mov_b32 vcc_lo, s71
	s_mov_b32 s71, s6
	v_mov_b32_e32 v198, v112
	s_branch .LBB0_396
.LBB0_404:
	v_max_f32_e32 v64, v64, v64
	v_max_f32_e32 v64, 0, v64
	v_exp_f32_e64 v229, -v64
	v_add_f32_e32 v199, v199, v64
	v_pk_add_f32 v[112:113], v[112:113], v[64:65] op_sel_hi:[1,0] neg_lo:[0,1] neg_hi:[0,1]
	v_pk_add_f32 v[96:97], v[96:97], v[64:65] op_sel_hi:[1,0] neg_lo:[0,1] neg_hi:[0,1]
	v_pk_add_f32 v[114:115], v[114:115], v[64:65] op_sel_hi:[1,0] neg_lo:[0,1] neg_hi:[0,1]
	v_pk_add_f32 v[98:99], v[98:99], v[64:65] op_sel_hi:[1,0] neg_lo:[0,1] neg_hi:[0,1]
	v_pk_add_f32 v[116:117], v[116:117], v[64:65] op_sel_hi:[1,0] neg_lo:[0,1] neg_hi:[0,1]
	v_pk_add_f32 v[100:101], v[100:101], v[64:65] op_sel_hi:[1,0] neg_lo:[0,1] neg_hi:[0,1]
	v_pk_add_f32 v[118:119], v[118:119], v[64:65] op_sel_hi:[1,0] neg_lo:[0,1] neg_hi:[0,1]
	v_pk_add_f32 v[102:103], v[102:103], v[64:65] op_sel_hi:[1,0] neg_lo:[0,1] neg_hi:[0,1]
	v_pk_add_f32 v[120:121], v[120:121], v[64:65] op_sel_hi:[1,0] neg_lo:[0,1] neg_hi:[0,1]
	v_pk_add_f32 v[104:105], v[104:105], v[64:65] op_sel_hi:[1,0] neg_lo:[0,1] neg_hi:[0,1]
	v_pk_add_f32 v[122:123], v[122:123], v[64:65] op_sel_hi:[1,0] neg_lo:[0,1] neg_hi:[0,1]
	v_pk_add_f32 v[106:107], v[106:107], v[64:65] op_sel_hi:[1,0] neg_lo:[0,1] neg_hi:[0,1]
	v_pk_add_f32 v[124:125], v[124:125], v[64:65] op_sel_hi:[1,0] neg_lo:[0,1] neg_hi:[0,1]
	v_pk_add_f32 v[108:109], v[108:109], v[64:65] op_sel_hi:[1,0] neg_lo:[0,1] neg_hi:[0,1]
	v_pk_add_f32 v[126:127], v[126:127], v[64:65] op_sel_hi:[1,0] neg_lo:[0,1] neg_hi:[0,1]
	v_pk_add_f32 v[110:111], v[110:111], v[64:65] op_sel_hi:[1,0] neg_lo:[0,1] neg_hi:[0,1]
	v_xor_b32_e32 v64, 0x80000000, v199
	v_mov_b32_e32 v80, v64
	v_mov_b32_e32 v81, v64
	v_mov_b32_e32 v82, v64
	v_mov_b32_e32 v83, v64
	v_mov_b32_e32 v84, v64
	v_mov_b32_e32 v85, v64
	v_mov_b32_e32 v86, v64
	v_mov_b32_e32 v87, v64
	v_mov_b32_e32 v88, v64
	v_mov_b32_e32 v89, v64
	v_mov_b32_e32 v90, v64
	v_mov_b32_e32 v91, v64
	v_mov_b32_e32 v92, v64
	v_mov_b32_e32 v93, v64
	v_mov_b32_e32 v94, v64
	v_mov_b32_e32 v95, v64
	s_branch .LBB0_398
; __device__ __forceinline__ void partialSM(f32x16& p0, f32x16& p1, float& m_ref, f32x16& negm, float& alpha, bool first) {
;     constexpr float THR2 = THR * 1.4426950408889634f;
;     float ma = p0[0], mb = p0[8], mc = p1[0], md = p1[8];
; #pragma unroll
;     for (int r = 1; r < 8; ++r) { ma = fmaxf(ma, p0[r]); mb = fmaxf(mb, p0[8 + r]); mc = fmaxf(mc, p1[r]); md = fmaxf(md, p1[8 + r]); }
;     float pmax = fmaxf(fmaxf(ma, mb), fmaxf(mc, md));
;     { auto rr = __builtin_amdgcn_permlane32_swap(__float_as_uint(pmax), __float_as_uint(pmax), false, false);
;       pmax = fmaxf(__uint_as_float(rr[0]), __uint_as_float(rr[1])); }
;     if (__builtin_expect(!first && __all(pmax <= THR2), 1)) { alpha = 1.f; }
; __device__ __forceinline__ void qkt(f32x16& p0, f32x16& p1, const char* Ks, const char* Krs, const bf16x8* qr, const char* qro, int r32, int hi, const f32x16& negm) {
;     p0 = negm; p1 = negm;
; #pragma unroll
;     for (int d0 = 0; d0 < 8; ++d0) { const int cb = (d0 * 16 + hi * 8) * 2;
;         const bf16x8 b0 = *reinterpret_cast<const bf16x8*>(Ks + KSWZ(r32, cb));
;         const bf16x8 b1 = *reinterpret_cast<const bf16x8*>(Ks + KSWZ(32 + r32, cb));
;         p0 = __builtin_amdgcn_mfma_f32_32x32x16_bf16(b0, qr[d0], p0, 0, 0, 0);
;         p1 = __builtin_amdgcn_mfma_f32_32x32x16_bf16(b1, qr[d0], p1, 0, 0, 0); }
; #pragma unroll
;     for (int d0 = 0; d0 < 4; ++d0) { const int cb = (d0 * 16 + hi * 8) * 2;
;         const bf16x8 b0 = *reinterpret_cast<const bf16x8*>(Krs + KRSWZ(r32, cb));
;         const bf16x8 b1 = *reinterpret_cast<const bf16x8*>(Krs + KRSWZ(32 + r32, cb));
;         const bf16x8 qf = qr[8 + d0];
;         p0 = __builtin_amdgcn_mfma_f32_32x32x16_bf16(b0, qf, p0, 0, 0, 0);
;         p1 = __builtin_amdgcn_mfma_f32_32x32x16_bf16(b1, qf, p1, 0, 0, 0); }
; }
.LBB0_405:
	v_mov_b64_e32 v[64:65], v[80:81]
	v_mov_b64_e32 v[66:67], v[82:83]
	v_mov_b64_e32 v[68:69], v[84:85]
	v_mov_b64_e32 v[70:71], v[86:87]
	v_mov_b64_e32 v[72:73], v[88:89]
	v_mov_b64_e32 v[74:75], v[90:91]
	v_mov_b64_e32 v[76:77], v[92:93]
	v_mov_b64_e32 v[78:79], v[94:95]
	s_add_i32 s28, s33, -1
	s_lshl_b64 s[6:7], s[28:29], 17
	v_add_u32_e32 v84, s72, v228
	v_lshl_add_u64 v[80:81], v[196:197], 0, s[6:7]
	v_lshl_add_u64 v[82:83], v[194:195], 0, s[6:7]
	v_readfirstlane_b32 s6, v84
	s_mov_b32 s7, m0
	s_mov_b32 m0, s6
	s_nop 0
	global_load_lds_dwordx4 v[82:83], off
	s_mov_b32 m0, s7
	s_addk_i32 s6, 0x400
	s_mov_b32 s7, m0
	s_mov_b32 m0, s6
	s_nop 0
	global_load_lds_dwordx4 v[80:81], off
	s_mov_b32 m0, s7
	s_add_i32 s7, s74, 0
	v_add3_u32 v100, s7, v227, v211
	ds_read_b128 v[96:99], v100
	ds_read_b128 v[114:117], v100 offset:8192
	v_add3_u32 v113, s7, v226, v211
	s_lshl_b32 s6, s70, 13
	s_waitcnt lgkmcnt(1)
	v_mfma_f32_32x32x16_bf16 v[80:95], v[96:99], v[128:131], v[64:79]
	s_waitcnt lgkmcnt(0)
	v_mfma_f32_32x32x16_bf16 v[96:111], v[114:117], v[128:131], v[64:79]
	ds_read_b128 v[114:117], v113
	s_waitcnt lgkmcnt(0)
	v_mfma_f32_32x32x16_bf16 v[80:95], v[114:117], v[132:135], v[80:95]
	ds_read_b128 v[114:117], v113 offset:8192
	v_add3_u32 v113, s7, v225, v211
	s_waitcnt lgkmcnt(0)
	v_mfma_f32_32x32x16_bf16 v[96:111], v[114:117], v[132:135], v[96:111]
	ds_read_b128 v[114:117], v113
	s_waitcnt lgkmcnt(0)
	v_mfma_f32_32x32x16_bf16 v[80:95], v[114:117], v[136:139], v[80:95]
	ds_read_b128 v[114:117], v113 offset:8192
	v_add3_u32 v113, s7, v224, v211
	s_waitcnt lgkmcnt(0)
	v_mfma_f32_32x32x16_bf16 v[96:111], v[114:117], v[136:139], v[96:111]
	ds_read_b128 v[114:117], v113
	s_waitcnt lgkmcnt(0)
	v_mfma_f32_32x32x16_bf16 v[80:95], v[114:117], v[140:143], v[80:95]
	ds_read_b128 v[114:117], v113 offset:8192
	v_add3_u32 v113, s7, v223, v211
	s_waitcnt lgkmcnt(0)
	v_mfma_f32_32x32x16_bf16 v[96:111], v[114:117], v[140:143], v[96:111]
	ds_read_b128 v[114:117], v113
	s_waitcnt lgkmcnt(0)
	v_mfma_f32_32x32x16_bf16 v[80:95], v[114:117], v[144:147], v[80:95]
	ds_read_b128 v[114:117], v113 offset:8192
	v_add3_u32 v113, s7, v222, v211
	s_waitcnt lgkmcnt(0)
	v_mfma_f32_32x32x16_bf16 v[96:111], v[114:117], v[144:147], v[96:111]
	ds_read_b128 v[114:117], v113
	s_waitcnt lgkmcnt(0)
	v_mfma_f32_32x32x16_bf16 v[80:95], v[114:117], v[148:151], v[80:95]
	ds_read_b128 v[114:117], v113 offset:8192
	v_add3_u32 v113, s7, v221, v211
	s_waitcnt lgkmcnt(0)
	v_mfma_f32_32x32x16_bf16 v[96:111], v[114:117], v[148:151], v[96:111]
	ds_read_b128 v[114:117], v113
	s_waitcnt lgkmcnt(0)
	v_mfma_f32_32x32x16_bf16 v[80:95], v[114:117], v[152:155], v[80:95]
	ds_read_b128 v[114:117], v113 offset:8192
	v_add3_u32 v113, s7, v220, v211
	s_sub_i32 s7, s7, s6
	s_waitcnt lgkmcnt(0)
	v_mfma_f32_32x32x16_bf16 v[96:111], v[114:117], v[152:155], v[96:111]
	ds_read_b128 v[114:117], v113
	s_waitcnt lgkmcnt(0)
	v_mfma_f32_32x32x16_bf16 v[80:95], v[114:117], v[156:159], v[80:95]
	ds_read_b128 v[114:117], v113 offset:8192
	v_add3_u32 v113, s7, v219, v215
	s_waitcnt lgkmcnt(0)
	v_mfma_f32_32x32x16_bf16 v[96:111], v[114:117], v[156:159], v[96:111]
	ds_read_b128 v[114:117], v113 offset:49152
	s_waitcnt lgkmcnt(0)
	v_mfma_f32_32x32x16_bf16 v[80:95], v[114:117], v[164:167], v[80:95]
	ds_read_b128 v[114:117], v113 offset:53248
	v_add3_u32 v113, s7, v218, v215
	s_waitcnt lgkmcnt(0)
	v_mfma_f32_32x32x16_bf16 v[96:111], v[114:117], v[164:167], v[96:111]
	ds_read_b128 v[114:117], v113 offset:49152
	s_waitcnt lgkmcnt(0)
	v_mfma_f32_32x32x16_bf16 v[80:95], v[114:117], v[172:175], v[80:95]
	ds_read_b128 v[114:117], v113 offset:53248
	v_add3_u32 v113, s7, v217, v215
	s_waitcnt lgkmcnt(0)
	v_mfma_f32_32x32x16_bf16 v[96:111], v[114:117], v[172:175], v[96:111]
	ds_read_b128 v[114:117], v113 offset:49152
	s_waitcnt lgkmcnt(0)
	v_mfma_f32_32x32x16_bf16 v[80:95], v[114:117], v[160:163], v[80:95]
	ds_read_b128 v[114:117], v113 offset:53248
	v_add3_u32 v113, s7, v216, v215
	s_waitcnt lgkmcnt(0)
	v_mfma_f32_32x32x16_bf16 v[96:111], v[114:117], v[160:163], v[96:111]
	ds_read_b128 v[114:117], v113 offset:49152
	s_waitcnt lgkmcnt(0)
	v_mfma_f32_32x32x16_bf16 v[80:95], v[114:117], v[168:171], v[80:95]
	ds_read_b128 v[114:117], v113 offset:53248
	s_waitcnt lgkmcnt(0)
	v_mfma_f32_32x32x16_bf16 v[96:111], v[114:117], v[168:171], v[96:111]
	s_nop 8
	v_max_f32_e32 v113, v81, v81
	v_max_f32_e32 v118, v80, v80
	v_max_f32_e32 v113, v118, v113
	v_max_f32_e32 v118, v89, v89
	v_max_f32_e32 v119, v88, v88
	v_max_f32_e32 v118, v119, v118
	v_max3_f32 v113, v113, v82, v83
	v_max_f32_e32 v114, v105, v105
	v_max_f32_e32 v115, v104, v104
	v_max_f32_e32 v114, v115, v114
	v_max3_f32 v115, v96, v97, v98
	v_max3_f32 v114, v114, v106, v107
	v_max3_f32 v116, v118, v90, v91
	v_max3_f32 v115, v115, v99, v100
	v_max3_f32 v114, v114, v108, v109
	v_max3_f32 v113, v113, v84, v85
	v_max3_f32 v116, v116, v92, v93
	v_max3_f32 v115, v115, v101, v102
	v_max3_f32 v114, v114, v110, v111
	v_max3_f32 v113, v113, v86, v87
	v_max3_f32 v116, v116, v94, v95
	v_max3_f32 v114, v115, v103, v114
	v_max3_f32 v113, v113, v116, v114
	v_mov_b32_e32 v114, v113
	s_nop 1
	v_permlane32_swap_b32_e32 v113, v114
	v_max_f32_e32 v114, v114, v114
	v_max_f32_e32 v113, v113, v113
	v_max_f32_e32 v114, v113, v114
	v_cmp_ge_f32_e32 vcc, s92, v114
	s_cmp_eq_u64 vcc, exec
	v_mov_b32_e32 v113, 1.0
	s_cbranch_scc0 .LBB0_423

; __global__ void __launch_bounds__(512, 2) fwd_kernel(Args args) {
;     extern __shared__ __attribute__((aligned(16))) unsigned char lds[];
	.amdhsa_kernel _Z10fwd_kernel4Args
		.amdhsa_group_segment_fixed_size 0
		.amdhsa_private_segment_fixed_size 0
		.amdhsa_kernarg_size 440
		.amdhsa_user_sgpr_count 2
		.amdhsa_user_sgpr_dispatch_ptr 0
		.amdhsa_user_sgpr_queue_ptr 0
		.amdhsa_user_sgpr_kernarg_segment_ptr 1
		.amdhsa_user_sgpr_dispatch_id 0
		.amdhsa_user_sgpr_kernarg_preload_length 0
		.amdhsa_user_sgpr_kernarg_preload_offset 0
		.amdhsa_user_sgpr_private_segment_size 0
		.amdhsa_uses_dynamic_stack 0
		.amdhsa_enable_private_segment 0
		.amdhsa_system_sgpr_workgroup_id_x 1
		.amdhsa_system_sgpr_workgroup_id_y 0
		.amdhsa_system_sgpr_workgroup_id_z 0
		.amdhsa_system_sgpr_workgroup_info 0
		.amdhsa_system_vgpr_workitem_id 2
		.amdhsa_next_free_vgpr 246
		.amdhsa_next_free_sgpr 100
		.amdhsa_accum_offset 248
		.amdhsa_reserve_vcc 1
		.amdhsa_float_round_mode_32 0
		.amdhsa_float_round_mode_16_64 0
		.amdhsa_float_denorm_mode_32 3
		.amdhsa_float_denorm_mode_16_64 3
		.amdhsa_dx10_clamp 1
		.amdhsa_ieee_mode 1
		.amdhsa_fp16_overflow 0
		.amdhsa_tg_split 0
		.amdhsa_exception_fp_ieee_invalid_op 0
		.amdhsa_exception_fp_denorm_src 0
		.amdhsa_exception_fp_ieee_div_zero 0
		.amdhsa_exception_fp_ieee_overflow 0
		.amdhsa_exception_fp_ieee_underflow 0
		.amdhsa_exception_fp_ieee_inexact 0
		.amdhsa_exception_int_div_zero 0
	.end_amdhsa_kernel

; __global__ void __launch_bounds__(512, 2) fwd_kernel(Args args) {
;     extern __shared__ __attribute__((aligned(16))) unsigned char lds[];
amdhsa.kernels:
  - .agpr_count:     0
    .args:
      - .offset:         0
        .size:           184
        .value_kind:     by_value
      - .offset:         184
        .size:           4
        .value_kind:     hidden_block_count_x
      - .offset:         188
        .size:           4
        .value_kind:     hidden_block_count_y
      - .offset:         192
        .size:           4
        .value_kind:     hidden_block_count_z
      - .offset:         196
        .size:           2
        .value_kind:     hidden_group_size_x
      - .offset:         198
        .size:           2
        .value_kind:     hidden_group_size_y
      - .offset:         200
        .size:           2
        .value_kind:     hidden_group_size_z
      - .offset:         202
        .size:           2
        .value_kind:     hidden_remainder_x
      - .offset:         204
        .size:           2
        .value_kind:     hidden_remainder_y
      - .offset:         206
        .size:           2
        .value_kind:     hidden_remainder_z
      - .offset:         224
        .size:           8
        .value_kind:     hidden_global_offset_x
      - .offset:         232
        .size:           8
        .value_kind:     hidden_global_offset_y
      - .offset:         240
        .size:           8
        .value_kind:     hidden_global_offset_z
      - .offset:         248
        .size:           2
        .value_kind:     hidden_grid_dims
      - .offset:         272
        .size:           8
        .value_kind:     hidden_multigrid_sync_arg
      - .offset:         304
        .size:           4
        .value_kind:     hidden_dynamic_lds_size
    .group_segment_fixed_size: 0
    .kernarg_segment_align: 8
    .kernarg_segment_size: 440
    .language:       OpenCL C
    .language_version:
      - 2
      - 0
    .max_flat_workgroup_size: 512
    .name:           _Z10fwd_kernel4Args
    .private_segment_fixed_size: 0
    .sgpr_count:     106
    .sgpr_spill_count: 35
    .symbol:         _Z10fwd_kernel4Args.kd
    .uniform_work_group_size: 1
    .uses_dynamic_stack: false
    .vgpr_count:     246
    .vgpr_spill_count: 0
    .wavefront_size: 64
